# phase 5: workgroups 64..255 hold their final y stores back by 3 x s_sleep 127 (on top of write-back stores)
# baseline (speedup 1.0000x reference)
.LBB0_1306:
	s_or_b64 exec, exec, s[0:1]
	s_cmp_lt_u32 s92, 64
	s_cbranch_scc1 .Lp5d_skip
	s_sleep 127
	s_sleep 127
	s_sleep 127
.Lp5d_skip:
	v_readlane_b32 s0, v251, 5
	v_readlane_b32 s12, v251, 17
	v_readlane_b32 s13, v251, 18
	v_readlane_b32 s14, v251, 19
	v_readlane_b32 s15, v251, 20
	v_lshl_add_u64 v[2:3], s[12:13], 0, v[66:67]
	v_lshl_add_u64 v[38:39], v[136:137], 2, s[82:83]
	v_lshl_add_u64 v[6:7], s[14:15], 0, v[66:67]
	s_barrier
	global_load_dwordx4 v[26:29], v[2:3], off
	global_load_dwordx4 v[18:21], v[2:3], off offset:64
	global_load_dwordx4 v[30:33], v[6:7], off
	global_load_dwordx4 v[22:25], v[6:7], off offset:64
	global_load_dwordx4 v[10:13], v[2:3], off offset:512
	s_nop 0
	global_load_dwordx4 v[2:5], v[2:3], off offset:576
	s_nop 0
	global_load_dwordx4 v[14:17], v[6:7], off offset:512
	s_nop 0
	global_load_dwordx4 v[6:9], v[6:7], off offset:576
	s_nop 0
	global_load_dword v41, v[144:145], off sc1
	global_load_dword v40, v[144:145], off offset:4 sc1
	global_load_dword v141, v[38:39], off sc1
	global_load_dword v140, v[38:39], off offset:4 sc1
	v_lshl_add_u64 v[38:39], v[146:147], 2, s[82:83]
	global_load_dword v147, v[38:39], off sc1
	global_load_dword v146, v[38:39], off offset:4 sc1
	v_lshl_add_u64 v[38:39], v[156:157], 2, s[82:83]
	global_load_dword v157, v[38:39], off sc1
	global_load_dword v156, v[38:39], off offset:4 sc1
	v_lshl_add_u64 v[38:39], v[158:159], 2, s[82:83]
	global_load_dword v195, v[38:39], off sc1
	global_load_dword v194, v[38:39], off offset:4 sc1
	v_or_b32_e32 v144, 16, v152
	v_lshlrev_b32_e32 v38, 1, v144
	v_ashrrev_i32_e32 v39, 31, v38
	v_lshl_add_u64 v[38:39], v[38:39], 2, s[82:83]
	global_load_dword v197, v[38:39], off sc1
	global_load_dword v196, v[38:39], off offset:4 sc1
	v_or_b32_e32 v136, 32, v152
	v_or_b32_e32 v38, 48, v152
	v_lshlrev_b32_e32 v158, 1, v136
	v_lshlrev_b32_e32 v192, 1, v38
	v_ashrrev_i32_e32 v159, 31, v158
	v_ashrrev_i32_e32 v193, 31, v192
	v_lshl_add_u64 v[158:159], v[158:159], 2, s[82:83]
	v_lshl_add_u64 v[192:193], v[192:193], 2, s[82:83]
	global_load_dword v199, v[158:159], off sc1
	global_load_dword v198, v[158:159], off offset:4 sc1
	global_load_dword v201, v[192:193], off sc1
	global_load_dword v200, v[192:193], off offset:4 sc1
	v_readlane_b32 s2, v251, 7
	v_readlane_b32 s3, v251, 8
	s_mov_b32 s2, 0x3a800000
	s_mov_b32 s3, 0x800000
	v_readlane_b32 s8, v251, 13
	v_readlane_b32 s9, v251, 14
	s_mov_b32 s8, 0x3727c5ac
	v_readlane_b32 s1, v251, 6
	v_readlane_b32 s4, v251, 9
	v_readlane_b32 s5, v251, 10
	v_readlane_b32 s6, v251, 11
	v_readlane_b32 s7, v251, 12
	v_lshlrev_b64 v[68:69], 12, v[68:69]
	v_lshl_add_u64 v[68:69], s[84:85], 0, v[68:69]
	v_lshl_add_u64 v[68:69], v[68:69], 0, v[66:67]
	v_lshlrev_b64 v[134:135], 12, v[134:135]
	v_lshl_add_u64 v[134:135], s[84:85], 0, v[134:135]
	v_lshl_add_u64 v[134:135], v[134:135], 0, v[66:67]
	v_readlane_b32 s10, v251, 15
	v_readlane_b32 s11, v251, 16
	s_waitcnt vmcnt(14)
	v_pk_mul_f32 v[206:207], v[40:41], s[2:3] op_sel_hi:[1,0]
	s_waitcnt vmcnt(12)
	v_pk_mul_f32 v[208:209], v[140:141], s[2:3] op_sel_hi:[1,0]
	v_mov_b32_e32 v41, v207
	v_mov_b32_e32 v40, v209
	v_mov_b32_e32 v140, v208
	v_mov_b32_e32 v141, v206
	v_pk_fma_f32 v[40:41], v[40:41], v[40:41], v[140:141] neg_lo:[1,0,0] neg_hi:[1,0,0]
	s_waitcnt vmcnt(10)
	v_pk_mul_f32 v[192:193], v[146:147], s[2:3] op_sel_hi:[1,0]
	s_waitcnt vmcnt(8)
	v_pk_mul_f32 v[158:159], v[156:157], s[2:3] op_sel_hi:[1,0]
	v_pk_add_f32 v[40:41], v[40:41], s[8:9] op_sel_hi:[1,0]
	s_waitcnt vmcnt(6)
	v_pk_mul_f32 v[156:157], v[194:195], s[2:3] op_sel_hi:[1,0]
	v_mov_b32_e32 v146, v159
	v_mov_b32_e32 v147, v193
	v_mov_b32_e32 v194, v158
	v_mov_b32_e32 v195, v192
	v_mul_f32_e32 v137, 0x4b800000, v40
	v_cmp_gt_f32_e64 s[0:1], s3, v40
	v_pk_fma_f32 v[140:141], v[146:147], v[146:147], v[194:195] neg_lo:[1,0,0] neg_hi:[1,0,0]
	v_mul_f32_e32 v39, 0x4b800000, v41
	v_cndmask_b32_e64 v40, v40, v137, s[0:1]
	v_pk_add_f32 v[140:141], v[140:141], s[8:9] op_sel_hi:[1,0]
	v_rsq_f32_e32 v40, v40
	v_mul_f32_e32 v145, 0x4b800000, v141
	v_cmp_gt_f32_e32 vcc, s3, v41
	v_cmp_gt_f32_e64 s[4:5], s3, v141
	s_waitcnt vmcnt(4)
	v_pk_mul_f32 v[146:147], v[196:197], s[2:3] op_sel_hi:[1,0]
	v_cndmask_b32_e32 v39, v41, v39, vcc
	v_cndmask_b32_e64 v41, v141, v145, s[4:5]
	v_rsq_f32_e32 v39, v39
	v_rsq_f32_e32 v41, v41
	v_mul_f32_e32 v141, 0x45800000, v40
	v_cndmask_b32_e64 v196, v40, v141, s[0:1]
	v_sub_f32_e32 v117, v117, v209
	v_sub_f32_e32 v116, v116, v209
	v_sub_f32_e32 v115, v115, v209
	v_sub_f32_e32 v114, v114, v209
	v_sub_f32_e32 v113, v113, v209
	v_sub_f32_e32 v112, v112, v209
	v_sub_f32_e32 v111, v111, v209
	v_sub_f32_e32 v110, v110, v209
	v_sub_f32_e32 v109, v109, v209
	v_sub_f32_e32 v108, v108, v209
	v_sub_f32_e32 v107, v107, v209
	v_sub_f32_e32 v106, v106, v209
	v_sub_f32_e32 v105, v105, v209
	v_sub_f32_e32 v104, v104, v209
	v_sub_f32_e32 v103, v103, v209
	v_sub_f32_e32 v102, v102, v209
	v_mov_b32_e32 v213, v156
	v_mul_f32_e32 v156, 0x4b800000, v140
	v_cmp_gt_f32_e64 s[6:7], s3, v140
	v_pk_mul_f32 v[114:115], v[114:115], v[196:197] op_sel_hi:[1,0]
	v_pk_mul_f32 v[116:117], v[116:117], v[196:197] op_sel_hi:[1,0]
	v_pk_mul_f32 v[110:111], v[110:111], v[196:197] op_sel_hi:[1,0]
	v_pk_mul_f32 v[112:113], v[112:113], v[196:197] op_sel_hi:[1,0]
	v_pk_mul_f32 v[106:107], v[106:107], v[196:197] op_sel_hi:[1,0]
	v_pk_mul_f32 v[108:109], v[108:109], v[196:197] op_sel_hi:[1,0]
	v_pk_mul_f32 v[102:103], v[102:103], v[196:197] op_sel_hi:[1,0]
	v_pk_mul_f32 v[104:105], v[104:105], v[196:197] op_sel_hi:[1,0]
	v_cndmask_b32_e64 v137, v140, v156, s[6:7]
	v_mul_f32_e32 v140, 0x45800000, v39
	v_mul_f32_e32 v145, 0x45800000, v41
	v_pk_fma_f32 v[116:117], v[28:29], v[116:117], v[32:33]
	v_pk_fma_f32 v[114:115], v[26:27], v[114:115], v[30:31]
	v_pk_fma_f32 v[112:113], v[20:21], v[112:113], v[24:25]
	v_pk_fma_f32 v[110:111], v[18:19], v[110:111], v[22:23]
	v_pk_fma_f32 v[108:109], v[12:13], v[108:109], v[16:17]
	v_pk_fma_f32 v[106:107], v[10:11], v[106:107], v[14:15]
	v_pk_fma_f32 v[104:105], v[4:5], v[104:105], v[8:9]
	v_pk_fma_f32 v[102:103], v[2:3], v[102:103], v[6:7]
	v_rsq_f32_e32 v137, v137
	v_cndmask_b32_e32 v194, v39, v140, vcc
	v_cndmask_b32_e64 v192, v41, v145, s[4:5]
	v_sub_f32_e32 v133, v133, v207
	v_sub_f32_e32 v132, v132, v207
	v_sub_f32_e32 v131, v131, v207
	v_sub_f32_e32 v130, v130, v207
	v_sub_f32_e32 v129, v129, v207
	v_sub_f32_e32 v128, v128, v207
	v_sub_f32_e32 v127, v127, v207
	v_sub_f32_e32 v126, v126, v207
	v_sub_f32_e32 v125, v125, v207
	v_sub_f32_e32 v124, v124, v207
	v_sub_f32_e32 v123, v123, v207
	v_sub_f32_e32 v122, v122, v207
	v_sub_f32_e32 v121, v121, v207
	v_sub_f32_e32 v120, v120, v207
	v_sub_f32_e32 v119, v119, v207
	v_sub_f32_e32 v118, v118, v207
	global_store_dwordx4 v[68:69], v[114:117], off
	global_store_dwordx4 v[68:69], v[110:113], off offset:64
	global_store_dwordx4 v[68:69], v[106:109], off offset:512
	global_store_dwordx4 v[68:69], v[102:105], off offset:576
	v_lshlrev_b64 v[68:69], 12, v[138:139]
	v_sub_f32_e32 v101, v101, v193
	v_sub_f32_e32 v100, v100, v193
	v_sub_f32_e32 v99, v99, v193
	v_sub_f32_e32 v98, v98, v193
	v_sub_f32_e32 v97, v97, v193
	v_sub_f32_e32 v96, v96, v193
	v_sub_f32_e32 v95, v95, v193
	v_sub_f32_e32 v94, v94, v193
	v_sub_f32_e32 v93, v93, v193
	v_sub_f32_e32 v92, v92, v193
	v_sub_f32_e32 v91, v91, v193
	v_sub_f32_e32 v90, v90, v193
	v_sub_f32_e32 v89, v89, v193
	v_sub_f32_e32 v88, v88, v193
	v_sub_f32_e32 v87, v87, v193
	v_sub_f32_e32 v86, v86, v193
	v_pk_mul_f32 v[130:131], v[130:131], v[194:195] op_sel_hi:[1,0]
	v_pk_mul_f32 v[132:133], v[132:133], v[194:195] op_sel_hi:[1,0]
	v_pk_mul_f32 v[126:127], v[126:127], v[194:195] op_sel_hi:[1,0]
	v_pk_mul_f32 v[128:129], v[128:129], v[194:195] op_sel_hi:[1,0]
	v_pk_mul_f32 v[122:123], v[122:123], v[194:195] op_sel_hi:[1,0]
	v_pk_mul_f32 v[124:125], v[124:125], v[194:195] op_sel_hi:[1,0]
	v_pk_mul_f32 v[118:119], v[118:119], v[194:195] op_sel_hi:[1,0]
	v_pk_mul_f32 v[120:121], v[120:121], v[194:195] op_sel_hi:[1,0]
	v_pk_mul_f32 v[98:99], v[98:99], v[192:193] op_sel_hi:[1,0]
	v_pk_mul_f32 v[100:101], v[100:101], v[192:193] op_sel_hi:[1,0]
	v_lshl_add_u64 v[68:69], s[84:85], 0, v[68:69]
	v_pk_mul_f32 v[94:95], v[94:95], v[192:193] op_sel_hi:[1,0]
	v_pk_mul_f32 v[96:97], v[96:97], v[192:193] op_sel_hi:[1,0]
	v_pk_mul_f32 v[90:91], v[90:91], v[192:193] op_sel_hi:[1,0]
	v_pk_mul_f32 v[92:93], v[92:93], v[192:193] op_sel_hi:[1,0]
	v_pk_mul_f32 v[86:87], v[86:87], v[192:193] op_sel_hi:[1,0]
	v_pk_mul_f32 v[88:89], v[88:89], v[192:193] op_sel_hi:[1,0]
	v_mov_b32_e32 v211, v157
	v_mov_b32_e32 v210, v147
	v_mov_b32_e32 v212, v146
	v_pk_fma_f32 v[132:133], v[28:29], v[132:133], v[32:33]
	v_pk_fma_f32 v[130:131], v[26:27], v[130:131], v[30:31]
	v_pk_fma_f32 v[128:129], v[20:21], v[128:129], v[24:25]
	v_pk_fma_f32 v[126:127], v[18:19], v[126:127], v[22:23]
	v_pk_fma_f32 v[124:125], v[12:13], v[124:125], v[16:17]
	v_pk_fma_f32 v[122:123], v[10:11], v[122:123], v[14:15]
	v_pk_fma_f32 v[120:121], v[4:5], v[120:121], v[8:9]
	v_pk_fma_f32 v[118:119], v[2:3], v[118:119], v[6:7]
	v_pk_fma_f32 v[100:101], v[28:29], v[100:101], v[32:33]
	v_pk_fma_f32 v[98:99], v[26:27], v[98:99], v[30:31]
	v_lshl_add_u64 v[68:69], v[68:69], 0, v[66:67]
	v_pk_fma_f32 v[96:97], v[20:21], v[96:97], v[24:25]
	v_pk_fma_f32 v[94:95], v[18:19], v[94:95], v[22:23]
	v_pk_fma_f32 v[92:93], v[12:13], v[92:93], v[16:17]
	v_pk_fma_f32 v[90:91], v[10:11], v[90:91], v[14:15]
	v_pk_fma_f32 v[88:89], v[4:5], v[88:89], v[8:9]
	v_pk_fma_f32 v[86:87], v[2:3], v[86:87], v[6:7]
	v_pk_fma_f32 v[40:41], v[210:211], v[210:211], v[212:213] neg_lo:[1,0,0] neg_hi:[1,0,0]
	global_store_dwordx4 v[134:135], v[130:133], off
	global_store_dwordx4 v[134:135], v[126:129], off offset:64
	global_store_dwordx4 v[134:135], v[122:125], off offset:512
	global_store_dwordx4 v[134:135], v[118:121], off offset:576
	global_store_dwordx4 v[68:69], v[98:101], off
	global_store_dwordx4 v[68:69], v[94:97], off offset:64
	global_store_dwordx4 v[68:69], v[90:93], off offset:512
	global_store_dwordx4 v[68:69], v[86:89], off offset:576
	v_lshlrev_b64 v[68:69], 12, v[142:143]
	v_mul_f32_e32 v146, 0x45800000, v137
	v_pk_add_f32 v[40:41], v[40:41], s[8:9] op_sel_hi:[1,0]
	v_lshl_add_u64 v[68:69], s[84:85], 0, v[68:69]
	v_mul_f32_e32 v39, 0x4b800000, v41
	v_cmp_gt_f32_e32 vcc, s3, v41
	v_cndmask_b32_e64 v158, v137, v146, s[6:7]
	v_lshl_add_u64 v[86:87], v[68:69], 0, v[66:67]
	v_sub_f32_e32 v69, v81, v159
	v_sub_f32_e32 v68, v80, v159
	v_cndmask_b32_e32 v39, v41, v39, vcc
	v_pk_mul_f32 v[68:69], v[68:69], v[158:159] op_sel_hi:[1,0]
	v_rsq_f32_e32 v39, v39
	v_mul_f32_e32 v41, 0x4b800000, v40
	v_cmp_gt_f32_e64 s[0:1], s3, v40
	v_pk_fma_f32 v[80:81], v[20:21], v[68:69], v[24:25]
	v_sub_f32_e32 v69, v77, v159
	v_sub_f32_e32 v68, v76, v159
	v_cndmask_b32_e64 v40, v40, v41, s[0:1]
	v_pk_mul_f32 v[68:69], v[68:69], v[158:159] op_sel_hi:[1,0]
	v_rsq_f32_e32 v145, v40
	v_pk_fma_f32 v[76:77], v[12:13], v[68:69], v[16:17]
	v_sub_f32_e32 v69, v73, v159
	v_sub_f32_e32 v68, v72, v159
	v_sub_f32_e32 v71, v71, v159
	v_sub_f32_e32 v70, v70, v159
	v_pk_mul_f32 v[72:73], v[70:71], v[158:159] op_sel_hi:[1,0]
	v_pk_mul_f32 v[68:69], v[68:69], v[158:159] op_sel_hi:[1,0]
	v_mul_f32_e32 v40, 0x45800000, v39
	v_pk_fma_f32 v[70:71], v[4:5], v[68:69], v[8:9]
	v_pk_fma_f32 v[68:69], v[2:3], v[72:73], v[6:7]
	v_cndmask_b32_e32 v156, v39, v40, vcc
	v_sub_f32_e32 v75, v75, v159
	v_sub_f32_e32 v74, v74, v159
	global_store_dwordx4 v[86:87], v[68:71], off offset:576
	v_sub_f32_e32 v57, v57, v157
	v_sub_f32_e32 v56, v56, v157
	v_lshlrev_b64 v[68:69], 12, v[152:153]
	v_sub_f32_e32 v55, v55, v157
	v_sub_f32_e32 v54, v54, v157
	v_sub_f32_e32 v53, v53, v157
	v_sub_f32_e32 v52, v52, v157
	v_sub_f32_e32 v51, v51, v157
	v_sub_f32_e32 v50, v50, v157
	v_mul_f32_e32 v39, 0x45800000, v145
	v_pk_mul_f32 v[74:75], v[74:75], v[158:159] op_sel_hi:[1,0]
	v_lshl_add_u64 v[68:69], s[84:85], 0, v[68:69]
	v_pk_mul_f32 v[54:55], v[54:55], v[156:157] op_sel_hi:[1,0]
	v_pk_mul_f32 v[56:57], v[56:57], v[156:157] op_sel_hi:[1,0]
	v_pk_mul_f32 v[50:51], v[50:51], v[156:157] op_sel_hi:[1,0]
	v_pk_mul_f32 v[52:53], v[52:53], v[156:157] op_sel_hi:[1,0]
	s_waitcnt vmcnt(15)
	v_pk_mul_f32 v[140:141], v[198:199], s[2:3] op_sel_hi:[1,0]
	s_waitcnt vmcnt(13)
	v_pk_mul_f32 v[40:41], v[200:201], s[2:3] op_sel_hi:[1,0]
	v_cndmask_b32_e64 v146, v145, v39, s[0:1]
	v_pk_fma_f32 v[74:75], v[10:11], v[74:75], v[14:15]
	v_lshl_add_u64 v[68:69], v[68:69], 0, v[66:67]
	v_pk_fma_f32 v[56:57], v[12:13], v[56:57], v[16:17]
	v_pk_fma_f32 v[54:55], v[10:11], v[54:55], v[14:15]
	v_pk_fma_f32 v[52:53], v[4:5], v[52:53], v[8:9]
	v_pk_fma_f32 v[50:51], v[2:3], v[50:51], v[6:7]
	v_ashrrev_i32_e32 v145, 31, v144
	v_mov_b32_e32 v198, v41
	v_mov_b32_e32 v199, v141
	v_mov_b32_e32 v200, v40
	v_mov_b32_e32 v201, v140
	v_sub_f32_e32 v85, v85, v159
	v_sub_f32_e32 v84, v84, v159
	v_sub_f32_e32 v83, v83, v159
	v_sub_f32_e32 v82, v82, v159
	global_store_dwordx4 v[86:87], v[74:77], off offset:512
	v_sub_f32_e32 v65, v65, v157
	v_sub_f32_e32 v64, v64, v157
	v_sub_f32_e32 v63, v63, v157
	v_sub_f32_e32 v62, v62, v157
	global_store_dwordx4 v[68:69], v[54:57], off offset:512
	global_store_dwordx4 v[68:69], v[50:53], off offset:576
	v_pk_fma_f32 v[198:199], v[198:199], v[198:199], v[200:201] neg_lo:[1,0,0] neg_hi:[1,0,0]
	v_lshlrev_b64 v[54:55], 12, v[144:145]
	v_sub_f32_e32 v51, v173, v147
	v_sub_f32_e32 v50, v172, v147
	v_sub_f32_e32 v53, v171, v147
	v_sub_f32_e32 v52, v170, v147
	v_pk_mul_f32 v[82:83], v[82:83], v[158:159] op_sel_hi:[1,0]
	v_pk_mul_f32 v[84:85], v[84:85], v[158:159] op_sel_hi:[1,0]
	v_pk_mul_f32 v[62:63], v[62:63], v[156:157] op_sel_hi:[1,0]
	v_pk_mul_f32 v[64:65], v[64:65], v[156:157] op_sel_hi:[1,0]
	v_pk_mul_f32 v[56:57], v[52:53], v[146:147] op_sel_hi:[1,0]
	v_pk_mul_f32 v[50:51], v[50:51], v[146:147] op_sel_hi:[1,0]
	v_lshl_add_u64 v[54:55], s[84:85], 0, v[54:55]
	v_pk_add_f32 v[198:199], v[198:199], s[8:9] op_sel_hi:[1,0]
	v_pk_fma_f32 v[84:85], v[28:29], v[84:85], v[32:33]
	v_pk_fma_f32 v[82:83], v[26:27], v[82:83], v[30:31]
	v_pk_fma_f32 v[64:65], v[28:29], v[64:65], v[32:33]
	v_pk_fma_f32 v[62:63], v[26:27], v[62:63], v[30:31]
	v_pk_fma_f32 v[52:53], v[28:29], v[50:51], v[32:33]
	v_pk_fma_f32 v[50:51], v[26:27], v[56:57], v[30:31]
	v_lshl_add_u64 v[54:55], v[54:55], 0, v[66:67]
	v_mul_f32_e32 v40, 0x4b800000, v199
	v_cmp_gt_f32_e32 vcc, s3, v199
	global_store_dwordx4 v[86:87], v[82:85], off
	v_sub_f32_e32 v79, v79, v159
	v_sub_f32_e32 v78, v78, v159
	global_store_dwordx4 v[68:69], v[62:65], off
	v_sub_f32_e32 v61, v61, v157
	v_sub_f32_e32 v60, v60, v157
	v_sub_f32_e32 v59, v59, v157
	v_sub_f32_e32 v58, v58, v157
	global_store_dwordx4 v[54:55], v[50:53], off
	v_cndmask_b32_e32 v40, v199, v40, vcc
	v_mul_f32_e32 v137, 0x4b800000, v198
	v_sub_f32_e32 v51, v165, v147
	v_sub_f32_e32 v50, v164, v147
	v_sub_f32_e32 v53, v161, v147
	v_sub_f32_e32 v52, v160, v147
	v_cmp_gt_f32_e64 s[4:5], s3, v198
	v_pk_mul_f32 v[78:79], v[78:79], v[158:159] op_sel_hi:[1,0]
	v_pk_mul_f32 v[58:59], v[58:59], v[156:157] op_sel_hi:[1,0]
	v_pk_mul_f32 v[60:61], v[60:61], v[156:157] op_sel_hi:[1,0]
	v_pk_mul_f32 v[56:57], v[52:53], v[146:147] op_sel_hi:[1,0]
	v_pk_mul_f32 v[50:51], v[50:51], v[146:147] op_sel_hi:[1,0]
	v_rsq_f32_e32 v40, v40
	v_cndmask_b32_e64 v137, v198, v137, s[4:5]
	v_pk_fma_f32 v[78:79], v[18:19], v[78:79], v[22:23]
	v_pk_fma_f32 v[60:61], v[20:21], v[60:61], v[24:25]
	v_pk_fma_f32 v[58:59], v[18:19], v[58:59], v[22:23]
	v_pk_fma_f32 v[52:53], v[20:21], v[50:51], v[24:25]
	v_pk_fma_f32 v[50:51], v[18:19], v[56:57], v[22:23]
	v_rsq_f32_e32 v137, v137
	global_store_dwordx4 v[86:87], v[78:81], off offset:64
	global_store_dwordx4 v[68:69], v[58:61], off offset:64
	global_store_dwordx4 v[54:55], v[50:53], off offset:64
	v_mul_f32_e32 v39, 0x45800000, v40
	v_cndmask_b32_e32 v140, v40, v39, vcc
	v_sub_f32_e32 v51, v169, v147
	v_sub_f32_e32 v50, v168, v147
	v_sub_f32_e32 v53, v167, v147
	v_sub_f32_e32 v52, v166, v147
	v_pk_mul_f32 v[56:57], v[52:53], v[146:147] op_sel_hi:[1,0]
	v_pk_mul_f32 v[50:51], v[50:51], v[146:147] op_sel_hi:[1,0]
	v_mul_f32_e32 v39, 0x45800000, v137
	v_pk_fma_f32 v[52:53], v[12:13], v[50:51], v[16:17]
	v_pk_fma_f32 v[50:51], v[10:11], v[56:57], v[14:15]
	global_store_dwordx4 v[54:55], v[50:53], off offset:512
	v_cndmask_b32_e64 v40, v137, v39, s[4:5]
	v_ashrrev_i32_e32 v137, 31, v136
	v_sub_f32_e32 v51, v177, v147
	v_sub_f32_e32 v50, v176, v147
	v_sub_f32_e32 v53, v175, v147
	v_sub_f32_e32 v52, v174, v147
	v_pk_mul_f32 v[56:57], v[52:53], v[146:147] op_sel_hi:[1,0]
	v_pk_mul_f32 v[50:51], v[50:51], v[146:147] op_sel_hi:[1,0]
	v_ashrrev_i32_e32 v39, 31, v38
	v_pk_fma_f32 v[52:53], v[4:5], v[50:51], v[8:9]
	v_pk_fma_f32 v[50:51], v[2:3], v[56:57], v[6:7]
	global_store_dwordx4 v[54:55], v[50:53], off offset:576
	v_lshlrev_b64 v[54:55], 12, v[136:137]
	v_lshl_add_u64 v[54:55], s[84:85], 0, v[54:55]
	v_sub_f32_e32 v51, v187, v141
	v_sub_f32_e32 v50, v186, v141
	v_sub_f32_e32 v53, v185, v141
	v_sub_f32_e32 v52, v184, v141
	v_pk_mul_f32 v[56:57], v[52:53], v[140:141] op_sel_hi:[1,0]
	v_pk_mul_f32 v[50:51], v[50:51], v[140:141] op_sel_hi:[1,0]
	v_lshl_add_u64 v[54:55], v[54:55], 0, v[66:67]
	v_pk_fma_f32 v[52:53], v[28:29], v[50:51], v[32:33]
	v_pk_fma_f32 v[50:51], v[26:27], v[56:57], v[30:31]
	global_store_dwordx4 v[54:55], v[50:53], off
	v_lshlrev_b64 v[38:39], 12, v[38:39]
	s_nop 0
	v_sub_f32_e32 v51, v179, v141
	v_sub_f32_e32 v50, v178, v141
	v_sub_f32_e32 v53, v155, v141
	v_sub_f32_e32 v52, v154, v141
	v_pk_mul_f32 v[56:57], v[52:53], v[140:141] op_sel_hi:[1,0]
	v_pk_mul_f32 v[50:51], v[50:51], v[140:141] op_sel_hi:[1,0]
	s_nop 0
	v_pk_fma_f32 v[52:53], v[20:21], v[50:51], v[24:25]
	v_pk_fma_f32 v[50:51], v[18:19], v[56:57], v[22:23]
	global_store_dwordx4 v[54:55], v[50:53], off offset:64
	s_nop 1
	v_sub_f32_e32 v51, v183, v141
	v_sub_f32_e32 v50, v182, v141
	v_sub_f32_e32 v53, v181, v141
	v_sub_f32_e32 v52, v180, v141
	v_pk_mul_f32 v[56:57], v[52:53], v[140:141] op_sel_hi:[1,0]
	v_pk_mul_f32 v[50:51], v[50:51], v[140:141] op_sel_hi:[1,0]
	s_nop 0
	v_pk_fma_f32 v[52:53], v[12:13], v[50:51], v[16:17]
	v_pk_fma_f32 v[50:51], v[10:11], v[56:57], v[14:15]
	global_store_dwordx4 v[54:55], v[50:53], off offset:512
	s_nop 1
	v_sub_f32_e32 v51, v191, v141
	v_sub_f32_e32 v50, v190, v141
	v_sub_f32_e32 v53, v189, v141
	v_sub_f32_e32 v52, v188, v141
	v_pk_mul_f32 v[56:57], v[52:53], v[140:141] op_sel_hi:[1,0]
	v_pk_mul_f32 v[50:51], v[50:51], v[140:141] op_sel_hi:[1,0]
	s_nop 0
	v_pk_fma_f32 v[52:53], v[4:5], v[50:51], v[8:9]
	v_pk_fma_f32 v[50:51], v[2:3], v[56:57], v[6:7]
	global_store_dwordx4 v[54:55], v[50:53], off offset:576
	s_nop 1
	v_sub_f32_e32 v53, v149, v41
	v_sub_f32_e32 v52, v148, v41
	v_sub_f32_e32 v51, v151, v41
	v_sub_f32_e32 v50, v150, v41
	v_pk_mul_f32 v[52:53], v[52:53], v[40:41] op_sel_hi:[1,0]
	v_pk_mul_f32 v[50:51], v[50:51], v[40:41] op_sel_hi:[1,0]
	v_pk_fma_f32 v[26:27], v[26:27], v[52:53], v[30:31]
	v_lshl_add_u64 v[30:31], s[84:85], 0, v[38:39]
	v_pk_fma_f32 v[28:29], v[28:29], v[50:51], v[32:33]
	v_lshl_add_u64 v[30:31], v[30:31], 0, v[66:67]
	global_store_dwordx4 v[30:31], v[26:29], off
	s_nop 1
	v_sub_f32_e32 v27, v49, v41
	v_sub_f32_e32 v26, v48, v41
	v_sub_f32_e32 v29, v47, v41
	v_sub_f32_e32 v28, v46, v41
	v_pk_mul_f32 v[28:29], v[28:29], v[40:41] op_sel_hi:[1,0]
	v_pk_mul_f32 v[26:27], v[26:27], v[40:41] op_sel_hi:[1,0]
	v_pk_fma_f32 v[18:19], v[18:19], v[28:29], v[22:23]
	v_pk_fma_f32 v[20:21], v[20:21], v[26:27], v[24:25]
	global_store_dwordx4 v[30:31], v[18:21], off offset:64
	s_nop 1
	v_sub_f32_e32 v19, v45, v41
	v_sub_f32_e32 v18, v44, v41
	v_sub_f32_e32 v21, v43, v41
	v_sub_f32_e32 v20, v42, v41
	v_pk_mul_f32 v[20:21], v[20:21], v[40:41] op_sel_hi:[1,0]
	v_pk_mul_f32 v[18:19], v[18:19], v[40:41] op_sel_hi:[1,0]
	v_pk_fma_f32 v[10:11], v[10:11], v[20:21], v[14:15]
	v_pk_fma_f32 v[12:13], v[12:13], v[18:19], v[16:17]
	global_store_dwordx4 v[30:31], v[10:13], off offset:512
	s_nop 1
	v_sub_f32_e32 v11, v37, v41
	v_sub_f32_e32 v10, v36, v41
	v_sub_f32_e32 v13, v35, v41
	v_sub_f32_e32 v12, v34, v41
	v_pk_mul_f32 v[12:13], v[12:13], v[40:41] op_sel_hi:[1,0]
	v_pk_mul_f32 v[10:11], v[10:11], v[40:41] op_sel_hi:[1,0]
	v_pk_fma_f32 v[2:3], v[2:3], v[12:13], v[6:7]
	v_pk_fma_f32 v[4:5], v[4:5], v[10:11], v[8:9]
	global_store_dwordx4 v[30:31], v[2:5], off offset:576
